# v44 + norm row-1 modulation batch issued early (no mid-item store drain) + prep GEMV k-loop weight loads one step ahead
# baseline (speedup 1.0000x reference)
; DI void ph_norm(const Params& p, int l, int bid, int nb) {
;     ...
;     for (int rr = 0; rr < 2; ++rr) {
;       const int row = it * 8 + rr * 4 + w;
;       const int b = row / NTOK, t = row % NTOK;
;       const float* src = xsrc_row(p, l, b, t);
;       mod[rr] = MOD + ((size_t)l * 9 + (t < NCTX ? 8 : b)) * 3072;
; #pragma unroll
;       for (int i = 0; i < 4; ++i) v[rr][i] = *(const float4*)(src + (i * 64 + lane) * 4);
;     }
; #pragma unroll
;     for (int rr = 0; rr < 2; ++rr) {
;       const int row = it * 8 + rr * 4 + w;
;       float ss = 0.f;
; #pragma unroll
;       for (int i = 0; i < 4; ++i) ss += v[rr][i].x * v[rr][i].x + v[rr][i].y * v[rr][i].y + v[rr][i].z * v[rr][i].z + v[rr][i].w * v[rr][i].w;
;       ss = wave_sum(ss);
.LBB0_115:
	s_or_b64 exec, exec, s[8:9]
	v_lshlrev_b64 v[8:9], v16, v[8:9]
	v_lshl_add_u64 v[8:9], v[18:19], 0, v[8:9]
	v_lshlrev_b64 v[10:11], 12, v[10:11]
	v_lshl_add_u64 v[8:9], v[8:9], 0, v[10:11]
	v_lshl_add_u64 v[8:9], v[8:9], 0, v[46:47]
	global_load_dwordx4 v[28:31], v[8:9], off
	global_load_dwordx4 v[20:23], v[8:9], off offset:1024
	global_load_dwordx4 v[16:19], v[8:9], off offset:2048
	s_nop 0
	global_load_dwordx4 v[8:11], v[8:9], off offset:3072
	v_add_u32_e32 v45, s2, v58
	s_waitcnt vmcnt(0) lgkmcnt(0)
	v_mov_b32_e32 v70, v25
	v_mov_b32_e32 v71, v13
	v_mov_b32_e32 v58, v24
	v_mov_b32_e32 v59, v12
	v_mov_b32_e32 v78, v5
	v_mov_b32_e32 v79, v1
	v_mul_hi_i32_i24_e32 v85, 0x3000, v45
	v_mul_i32_i24_e32 v84, 0x3000, v45
	v_pk_mul_f32 v[70:71], v[70:71], v[70:71]
	v_mov_b32_e32 v72, v26
	v_mov_b32_e32 v73, v14
	v_mov_b32_e32 v76, v4
	v_mov_b32_e32 v77, v0
	v_pk_mul_f32 v[78:79], v[78:79], v[78:79]
	v_lshl_add_u64 v[84:85], s[0:1], 0, v[84:85]
	v_pk_fma_f32 v[58:59], v[58:59], v[58:59], v[70:71]
	s_mov_b64 s[12:13], 0x1000
	v_mov_b32_e32 v74, v27
	v_mov_b32_e32 v75, v15
	v_mov_b32_e32 v80, v6
	v_mov_b32_e32 v81, v2
	v_pk_fma_f32 v[70:71], v[76:77], v[76:77], v[78:79]
	v_pk_fma_f32 v[58:59], v[72:73], v[72:73], v[58:59]
	v_lshl_add_u64 v[78:79], v[84:85], 0, s[12:13]
	v_mov_b32_e32 v82, v7
	v_mov_b32_e32 v83, v3
	v_pk_fma_f32 v[70:71], v[80:81], v[80:81], v[70:71]
	v_lshl_add_u64 v[80:81], v[84:85], 0, v[46:47]
	v_pk_fma_f32 v[58:59], v[74:75], v[74:75], v[58:59]
	v_lshl_add_u64 v[74:75], v[78:79], 0, v[46:47]
	v_mov_b64_e32 v[66:67], v[104:105]
	v_mov_b64_e32 v[68:69], v[106:107]
	v_pk_fma_f32 v[82:83], v[82:83], v[82:83], v[70:71]
	global_load_dwordx4 v[70:73], v[80:81], off
	global_load_dwordx4 v[120:123], v[80:81], off offset:1024
	global_load_dwordx4 v[124:127], v[80:81], off offset:2048
	global_load_dwordx4 v[128:131], v[80:81], off offset:3072
	s_nop 0
	global_load_dwordx4 v[132:135], v[74:75], off offset:1024
	global_load_dwordx4 v[136:139], v[74:75], off offset:2048
	global_load_dwordx4 v[140:143], v[74:75], off offset:3072
	global_load_dwordx4 v[74:77], v[74:75], off
	v_add_u32_e32 v204, s2, v56
	v_mul_hi_i32_i24_e32 v207, 0x3000, v204
	v_mul_i32_i24_e32 v206, 0x3000, v204
	v_lshl_add_u64 v[206:207], s[0:1], 0, v[206:207]
	v_lshl_add_u64 v[208:209], v[206:207], 0, v[46:47]
	v_lshl_add_u64 v[206:207], v[206:207], 0, s[12:13]
	v_lshl_add_u64 v[206:207], v[206:207], 0, v[46:47]
	global_load_dwordx4 v[212:215], v[208:209], off
	global_load_dwordx4 v[156:159], v[208:209], off offset:1024
	global_load_dwordx4 v[196:199], v[208:209], off offset:2048
	global_load_dwordx4 v[200:203], v[208:209], off offset:3072
	global_load_dwordx4 v[216:219], v[206:207], off
	global_load_dwordx4 v[144:147], v[206:207], off offset:1024
	global_load_dwordx4 v[148:151], v[206:207], off offset:2048
	global_load_dwordx4 v[152:155], v[206:207], off offset:3072
	v_mov_b32_e32 v85, v58
	v_mov_b32_e32 v87, v82
	s_mov_b32 s8, 0x3a800000
	v_ashrrev_i32_e32 v45, 31, v44
	s_add_i32 s10, s10, s54
	s_mov_b32 s38, 0x800000
	s_cmpk_lt_i32 s10, 0x900
	v_mov_b32_e32 v94, v29
	v_mov_b32_e32 v95, v21
	v_mov_b32_e32 v92, v28
	v_mov_b32_e32 v93, v20
	v_mov_b32_e32 v102, v17
	v_mov_b32_e32 v103, v9
	v_pk_mul_f32 v[94:95], v[94:95], v[94:95]
	v_mov_b32_e32 v88, v30
	v_mov_b32_e32 v89, v22
	v_mov_b32_e32 v100, v16
	v_mov_b32_e32 v101, v8
	v_pk_mul_f32 v[102:103], v[102:103], v[102:103]
	v_pk_fma_f32 v[92:93], v[92:93], v[92:93], v[94:95]
	v_mov_b32_e32 v90, v31
	v_mov_b32_e32 v91, v23
	v_mov_b32_e32 v96, v18
	v_mov_b32_e32 v97, v10
	v_pk_fma_f32 v[94:95], v[100:101], v[100:101], v[102:103]
	v_pk_fma_f32 v[88:89], v[88:89], v[88:89], v[92:93]
	v_mov_b32_e32 v98, v19
	v_mov_b32_e32 v99, v11
	v_pk_fma_f32 v[92:93], v[96:97], v[96:97], v[94:95]
	v_pk_fma_f32 v[88:89], v[90:91], v[90:91], v[88:89]
	v_pk_fma_f32 v[90:91], v[98:99], v[98:99], v[92:93]
	v_mov_b32_e32 v84, v88
	v_mov_b32_e32 v58, v89
	v_mov_b32_e32 v86, v90
	v_pk_add_f32 v[58:59], v[84:85], v[58:59]
	v_mov_b32_e32 v82, v91
	v_pk_add_f32 v[58:59], v[58:59], v[86:87]
	v_lshl_add_u64 v[84:85], v[44:45], 0, v[36:37]
	v_pk_add_f32 v[58:59], v[58:59], v[82:83]
	v_mov_b32_e32 v82, v58
	v_mov_b32_e32 v83, v59
	v_lshlrev_b64 v[84:85], 6, v[84:85]
	v_lshl_add_u64 v[84:85], v[32:33], 0, v[84:85]
	v_permlane32_swap_b32_e32 v82, v58
	v_permlane32_swap_b32_e32 v83, v59
	v_pk_add_f32 v[58:59], v[58:59], v[82:83]
	v_mov_b32_e32 v82, v58
	v_mov_b32_e32 v83, v59
	s_nop 1
	v_permlane16_swap_b32_e32 v82, v58
	v_permlane16_swap_b32_e32 v83, v59
	v_pk_add_f32 v[58:59], v[58:59], v[82:83]
	s_nop 1
	v_add_f32_dpp v58, v58, v58 row_ror:8 row_mask:0xf bank_mask:0xf
	v_add_f32_dpp v59, v59, v59 row_ror:8 row_mask:0xf bank_mask:0xf
	s_nop 0
	v_add_f32_dpp v82, v58, v58 row_shl:4 row_mask:0xf bank_mask:0x5
	v_add_f32_dpp v83, v59, v59 row_shl:4 row_mask:0xf bank_mask:0x5
	v_add_f32_dpp v82, v58, v58 row_shr:4 row_mask:0xf bank_mask:0xa
	v_add_f32_dpp v83, v59, v59 row_shr:4 row_mask:0xf bank_mask:0xa
	s_nop 0
	v_add_f32_dpp v58, v82, v82 quad_perm:[2,3,0,1] row_mask:0xf bank_mask:0xf
	v_add_f32_dpp v59, v83, v83 quad_perm:[2,3,0,1] row_mask:0xf bank_mask:0xf
	s_nop 0
	v_add_f32_dpp v58, v58, v58 quad_perm:[1,0,3,2] row_mask:0xf bank_mask:0xf
	v_add_f32_dpp v59, v59, v59 quad_perm:[1,0,3,2] row_mask:0xf bank_mask:0xf
	s_waitcnt vmcnt(0)
; DI size_t kblk(int row, int col, int nrows) { return ((size_t)(col >> 5) * nrows + row) * 32 + (col & 31); }
; DI unsigned pk2(float a, float b) { hwf32x2 f = {a, b}; hwbf16x2 r = __builtin_convertvector(f, hwbf16x2); return __builtin_bit_cast(unsigned, r); }
; DI void ph_norm(const Params& p, int l, int bid, int nb) {
;     ...
;       for (int i = 0; i < 4; ++i) {
;         const int j = (i * 64 + lane) * 4;
;         const float4 gg = *(const float4*)(g + j);
;         const float4 sh = *(const float4*)(mod[rr] + j);
;         const float4 sc = *(const float4*)(mod[rr] + 1024 + j);
;         uint2 o;
;         o.x = pk2(v[rr][i].x * rstd * gg.x * (1.f + sc.x) + sh.x, v[rr][i].y * rstd * gg.y * (1.f + sc.y) + sh.y);
;         o.y = pk2(v[rr][i].z * rstd * gg.z * (1.f + sc.z) + sh.z, v[rr][i].w * rstd * gg.w * (1.f + sc.w) + sh.w);
;         *(uint2*)(H + kblk(row, j, ROWS)) = o;
	v_pk_add_f32 v[74:75], v[74:75], 1.0 op_sel_hi:[1,0]
	v_pk_add_f32 v[76:77], v[76:77], 1.0 op_sel_hi:[1,0]
	s_nop 0
	v_pk_fma_f32 v[58:59], v[58:59], s[8:9], v[162:163] op_sel_hi:[1,0,0]
	s_mov_b32 s8, 0x800000
	v_mul_f32_e32 v55, 0x4b800000, v59
	v_cmp_gt_f32_e32 vcc, s8, v59
	v_lshl_add_u64 v[82:83], v[78:79], 0, v[48:49]
	s_nop 0
	v_cndmask_b32_e32 v55, v59, v55, vcc
	v_rsq_f32_e32 v55, v55
	s_nop 0
	v_mul_f32_e32 v57, 0x45800000, v55
	v_cndmask_b32_e32 v86, v55, v57, vcc
	v_pk_mul_f32 v[24:25], v[24:25], v[86:87] op_sel_hi:[1,0]
	v_pk_mul_f32 v[26:27], v[26:27], v[86:87] op_sel_hi:[1,0]
	v_pk_mul_f32 v[24:25], v[66:67], v[24:25]
	v_pk_mul_f32 v[26:27], v[68:69], v[26:27]
	v_pk_fma_f32 v[24:25], v[74:75], v[24:25], v[70:71]
	v_pk_fma_f32 v[26:27], v[26:27], v[76:77], v[72:73]
	v_cvt_pk_bf16_f32 v24, v24, v25
	v_cvt_pk_bf16_f32 v25, v26, v27
	global_store_dwordx2 v[84:85], v[24:25], off
	v_mov_b64_e32 v[24:25], v[108:109]
	v_mov_b64_e32 v[26:27], v[110:111]
	s_nop 0
	v_mov_b64_e32 v[66:67], v[132:133]
	v_mov_b64_e32 v[68:69], v[134:135]
	v_mov_b64_e32 v[70:71], v[120:121]
	v_mov_b64_e32 v[72:73], v[122:123]
	v_pk_mul_f32 v[12:13], v[12:13], v[86:87] op_sel_hi:[1,0]
	v_pk_mul_f32 v[14:15], v[14:15], v[86:87] op_sel_hi:[1,0]
	v_lshl_add_u64 v[74:75], v[44:45], 0, v[38:39]
	v_lshlrev_b64 v[74:75], 6, v[74:75]
	v_lshl_add_u64 v[74:75], v[32:33], 0, v[74:75]
	v_lshl_add_u64 v[76:77], v[78:79], 0, v[50:51]
	v_pk_mul_f32 v[4:5], v[4:5], v[86:87] op_sel_hi:[1,0]
	v_pk_mul_f32 v[6:7], v[6:7], v[86:87] op_sel_hi:[1,0]
	v_pk_mul_f32 v[0:1], v[0:1], v[86:87] op_sel_hi:[1,0]
	v_pk_mul_f32 v[2:3], v[2:3], v[86:87] op_sel_hi:[1,0]
	v_add_u32_e32 v55, s2, v56
	v_mul_hi_i32_i24_e32 v57, 0x3000, v55
	v_mul_i32_i24_e32 v56, 0x3000, v55
	v_lshl_add_u64 v[56:57], s[0:1], 0, v[56:57]
	v_cmp_gt_f32_e32 vcc, s8, v58
	v_ashrrev_i32_e32 v55, 31, v54
	v_readlane_b32 s8, v254, 11
	v_pk_mul_f32 v[12:13], v[12:13], v[24:25]
	s_waitcnt lgkmcnt(0)
	v_pk_add_f32 v[24:25], v[66:67], 1.0 op_sel_hi:[1,0]
	v_pk_mul_f32 v[14:15], v[14:15], v[26:27]
	v_pk_add_f32 v[26:27], v[68:69], 1.0 op_sel_hi:[1,0]
	v_pk_fma_f32 v[12:13], v[12:13], v[24:25], v[70:71]
	v_pk_fma_f32 v[14:15], v[14:15], v[26:27], v[72:73]
	v_cvt_pk_bf16_f32 v12, v12, v13
	v_cvt_pk_bf16_f32 v13, v14, v15
	global_store_dwordx2 v[74:75], v[12:13], off
	v_mov_b64_e32 v[12:13], v[112:113]
	v_mov_b64_e32 v[14:15], v[114:115]
	s_nop 0
	v_mov_b64_e32 v[24:25], v[136:137]
	v_mov_b64_e32 v[26:27], v[138:139]
	v_mov_b64_e32 v[66:67], v[124:125]
	v_mov_b64_e32 v[68:69], v[126:127]
	v_lshl_add_u64 v[70:71], v[44:45], 0, v[40:41]
	v_lshlrev_b64 v[70:71], 6, v[70:71]
	v_lshl_add_u64 v[70:71], v[32:33], 0, v[70:71]
	v_lshl_add_u64 v[72:73], v[78:79], 0, v[52:53]
	v_pk_mul_f32 v[4:5], v[4:5], v[12:13]
	s_waitcnt lgkmcnt(0)
	v_pk_add_f32 v[12:13], v[24:25], 1.0 op_sel_hi:[1,0]
	v_pk_mul_f32 v[6:7], v[6:7], v[14:15]
	v_pk_add_f32 v[14:15], v[26:27], 1.0 op_sel_hi:[1,0]
	v_pk_fma_f32 v[4:5], v[4:5], v[12:13], v[66:67]
	v_pk_fma_f32 v[6:7], v[6:7], v[14:15], v[68:69]
	v_cvt_pk_bf16_f32 v4, v4, v5
	v_cvt_pk_bf16_f32 v5, v6, v7
	global_store_dwordx2 v[70:71], v[4:5], off
	v_mov_b64_e32 v[4:5], v[116:117]
	v_mov_b64_e32 v[6:7], v[118:119]
	s_nop 0
	v_mov_b64_e32 v[12:13], v[140:141]
	v_mov_b64_e32 v[14:15], v[142:143]
	v_mov_b64_e32 v[24:25], v[128:129]
	v_mov_b64_e32 v[26:27], v[130:131]
	v_lshl_add_u64 v[66:67], v[44:45], 0, v[42:43]
	v_lshlrev_b64 v[66:67], 6, v[66:67]
	v_lshl_add_u64 v[66:67], v[32:33], 0, v[66:67]
	v_lshl_add_u64 v[68:69], v[56:57], 0, s[12:13]
	v_lshl_add_u64 v[70:71], v[68:69], 0, v[46:47]
	v_mul_f32_e32 v45, 0x4b800000, v58
	v_cndmask_b32_e32 v45, v58, v45, vcc
	v_rsq_f32_e32 v45, v45
	v_add_u32_e32 v44, s8, v44
	v_mul_f32_e32 v58, 0x45800000, v45
	v_cndmask_b32_e32 v58, v45, v58, vcc
	v_pk_mul_f32 v[28:29], v[28:29], v[58:59] op_sel_hi:[1,0]
	v_pk_mul_f32 v[30:31], v[30:31], v[58:59] op_sel_hi:[1,0]
	v_pk_mul_f32 v[20:21], v[20:21], v[58:59] op_sel_hi:[1,0]
	v_pk_mul_f32 v[22:23], v[22:23], v[58:59] op_sel_hi:[1,0]
	v_pk_mul_f32 v[16:17], v[16:17], v[58:59] op_sel_hi:[1,0]
	v_pk_mul_f32 v[18:19], v[18:19], v[58:59] op_sel_hi:[1,0]
	v_pk_mul_f32 v[8:9], v[8:9], v[58:59] op_sel_hi:[1,0]
	v_pk_mul_f32 v[10:11], v[10:11], v[58:59] op_sel_hi:[1,0]
	v_pk_mul_f32 v[0:1], v[0:1], v[4:5]
	s_waitcnt lgkmcnt(0)
; DI size_t kblk(int row, int col, int nrows) { return ((size_t)(col >> 5) * nrows + row) * 32 + (col & 31); }
; DI unsigned pk2(float a, float b) { hwf32x2 f = {a, b}; hwbf16x2 r = __builtin_convertvector(f, hwbf16x2); return __builtin_bit_cast(unsigned, r); }
; DI void ph_norm(const Params& p, int l, int bid, int nb) {
;     ...
; #pragma unroll
;       for (int i = 0; i < 4; ++i) {
;         const int j = (i * 64 + lane) * 4;
;         const float4 gg = *(const float4*)(g + j);
;         const float4 sh = *(const float4*)(mod[rr] + j);
;         const float4 sc = *(const float4*)(mod[rr] + 1024 + j);
;         uint2 o;
;         o.x = pk2(v[rr][i].x * rstd * gg.x * (1.f + sc.x) + sh.x, v[rr][i].y * rstd * gg.y * (1.f + sc.y) + sh.y);
;         o.y = pk2(v[rr][i].z * rstd * gg.z * (1.f + sc.z) + sh.z, v[rr][i].w * rstd * gg.w * (1.f + sc.w) + sh.w);
;         *(uint2*)(H + kblk(row, j, ROWS)) = o;
	v_pk_add_f32 v[4:5], v[12:13], 1.0 op_sel_hi:[1,0]
	v_pk_mul_f32 v[2:3], v[2:3], v[6:7]
	v_pk_add_f32 v[6:7], v[14:15], 1.0 op_sel_hi:[1,0]
	v_pk_fma_f32 v[0:1], v[0:1], v[4:5], v[24:25]
	v_pk_fma_f32 v[2:3], v[2:3], v[6:7], v[26:27]
	v_cvt_pk_bf16_f32 v0, v0, v1
	v_cvt_pk_bf16_f32 v1, v2, v3
	global_store_dwordx2 v[66:67], v[0:1], off
	v_mov_b64_e32 v[0:1], v[104:105]
	v_mov_b64_e32 v[2:3], v[106:107]
	s_nop 0
	v_mov_b64_e32 v[4:5], v[216:217]
	v_mov_b64_e32 v[6:7], v[218:219]
	v_lshl_add_u64 v[24:25], v[56:57], 0, v[46:47]
	v_mov_b64_e32 v[12:13], v[212:213]
	v_mov_b64_e32 v[14:15], v[214:215]
	v_lshl_add_u64 v[26:27], v[54:55], 0, v[36:37]
	v_lshlrev_b64 v[26:27], 6, v[26:27]
	v_lshl_add_u64 v[26:27], v[32:33], 0, v[26:27]
	v_lshl_add_u64 v[56:57], v[68:69], 0, v[48:49]
	v_pk_mul_f32 v[0:1], v[0:1], v[28:29]
	s_waitcnt lgkmcnt(0)
	v_pk_add_f32 v[4:5], v[4:5], 1.0 op_sel_hi:[1,0]
	v_pk_mul_f32 v[2:3], v[2:3], v[30:31]
	v_pk_add_f32 v[6:7], v[6:7], 1.0 op_sel_hi:[1,0]
	v_pk_fma_f32 v[0:1], v[4:5], v[0:1], v[12:13]
	v_pk_fma_f32 v[2:3], v[2:3], v[6:7], v[14:15]
	v_cvt_pk_bf16_f32 v0, v0, v1
	v_cvt_pk_bf16_f32 v1, v2, v3
	global_store_dwordx2 v[26:27], v[0:1], off
	v_mov_b64_e32 v[0:1], v[108:109]
	v_mov_b64_e32 v[2:3], v[110:111]
	s_nop 0
	v_mov_b64_e32 v[4:5], v[144:145]
	v_mov_b64_e32 v[6:7], v[146:147]
	v_mov_b64_e32 v[12:13], v[156:157]
	v_mov_b64_e32 v[14:15], v[158:159]
	v_lshl_add_u64 v[26:27], v[54:55], 0, v[38:39]
	v_lshlrev_b64 v[26:27], 6, v[26:27]
	v_lshl_add_u64 v[26:27], v[32:33], 0, v[26:27]
	v_lshl_add_u64 v[28:29], v[68:69], 0, v[50:51]
	v_pk_mul_f32 v[0:1], v[20:21], v[0:1]
	s_waitcnt lgkmcnt(0)
	v_pk_add_f32 v[4:5], v[4:5], 1.0 op_sel_hi:[1,0]
	v_pk_mul_f32 v[2:3], v[22:23], v[2:3]
	v_pk_add_f32 v[6:7], v[6:7], 1.0 op_sel_hi:[1,0]
	v_pk_fma_f32 v[0:1], v[0:1], v[4:5], v[12:13]
	v_pk_fma_f32 v[2:3], v[2:3], v[6:7], v[14:15]
	v_cvt_pk_bf16_f32 v0, v0, v1
	v_cvt_pk_bf16_f32 v1, v2, v3
	global_store_dwordx2 v[26:27], v[0:1], off
	v_mov_b64_e32 v[0:1], v[112:113]
	v_mov_b64_e32 v[2:3], v[114:115]
	s_nop 0
	v_mov_b64_e32 v[4:5], v[148:149]
	v_mov_b64_e32 v[6:7], v[150:151]
	v_mov_b64_e32 v[12:13], v[196:197]
	v_mov_b64_e32 v[14:15], v[198:199]
	v_lshl_add_u64 v[20:21], v[54:55], 0, v[40:41]
	v_lshlrev_b64 v[20:21], 6, v[20:21]
	v_lshl_add_u64 v[20:21], v[32:33], 0, v[20:21]
	v_lshl_add_u64 v[22:23], v[68:69], 0, v[52:53]
	v_pk_mul_f32 v[0:1], v[16:17], v[0:1]
	s_waitcnt lgkmcnt(0)
	v_pk_add_f32 v[4:5], v[4:5], 1.0 op_sel_hi:[1,0]
	v_pk_mul_f32 v[2:3], v[18:19], v[2:3]
	v_pk_add_f32 v[6:7], v[6:7], 1.0 op_sel_hi:[1,0]
	v_pk_fma_f32 v[0:1], v[0:1], v[4:5], v[12:13]
	v_pk_fma_f32 v[2:3], v[2:3], v[6:7], v[14:15]
	v_cvt_pk_bf16_f32 v0, v0, v1
	v_cvt_pk_bf16_f32 v1, v2, v3
	global_store_dwordx2 v[20:21], v[0:1], off
	v_mov_b64_e32 v[0:1], v[116:117]
	v_mov_b64_e32 v[2:3], v[118:119]
	s_nop 0
	v_mov_b64_e32 v[4:5], v[152:153]
	v_mov_b64_e32 v[6:7], v[154:155]
	v_mov_b64_e32 v[12:13], v[200:201]
	v_mov_b64_e32 v[14:15], v[202:203]
	v_lshl_add_u64 v[16:17], v[54:55], 0, v[42:43]
	v_lshlrev_b64 v[16:17], 6, v[16:17]
	v_lshl_add_u64 v[16:17], v[32:33], 0, v[16:17]
	v_pk_mul_f32 v[0:1], v[8:9], v[0:1]
	s_waitcnt lgkmcnt(0)
	v_pk_add_f32 v[4:5], v[4:5], 1.0 op_sel_hi:[1,0]
	v_pk_mul_f32 v[2:3], v[10:11], v[2:3]
	v_pk_add_f32 v[6:7], v[6:7], 1.0 op_sel_hi:[1,0]
	v_pk_fma_f32 v[0:1], v[0:1], v[4:5], v[12:13]
	v_pk_fma_f32 v[2:3], v[2:3], v[6:7], v[14:15]
	v_cvt_pk_bf16_f32 v0, v0, v1
	v_cvt_pk_bf16_f32 v1, v2, v3
	global_store_dwordx2 v[16:17], v[0:1], off
	s_cbranch_scc0 .LBB0_124
